# attention loop: packed v_pk_fma_f32 beside MFMAs split into scalar v_fmamk pairs (docs 7.5 packed-vs-scalar lever)
# speedup vs baseline: 1.0097x; 1.0097x over previous
.LBB0_433:
	ds_read_b128 v[64:67], v166 offset:49152
	ds_read_b128 v[68:71], v166 offset:57344
	ds_read_b128 v[176:179], v167 offset:49152
	ds_read_b128 v[198:201], v167 offset:57344
	ds_read_b128 v[202:205], v168 offset:49152
	ds_read_b128 v[210:213], v168 offset:57344
	v_exp_f32_e32 v142, v142
	v_exp_f32_e32 v143, v143
	s_waitcnt lgkmcnt(5)
	v_mfma_f32_32x32x16_bf16 v[80:95], v[64:67], v[124:127], 0
	v_exp_f32_e32 v180, v140
	v_exp_f32_e32 v181, v141
	v_exp_f32_e32 v206, v138
	v_exp_f32_e32 v207, v135
	v_exp_f32_e32 v148, v148
	v_exp_f32_e32 v149, v149
	v_exp_f32_e32 v209, v146
	s_waitcnt lgkmcnt(4)
	v_mfma_f32_32x32x16_bf16 v[64:79], v[68:71], v[124:127], 0
	v_cvt_pk_bf16_f32 v135, v192, v193
	v_cvt_pk_bf16_f32 v138, v182, v183
	v_cvt_pk_bf16_f32 v140, v185, v187
	v_cvt_pk_bf16_f32 v141, v188, v189
	s_nop 0
	s_waitcnt lgkmcnt(3)
	v_mfma_f32_32x32x16_bf16 v[80:95], v[176:179], v[120:123], v[80:95]
	ds_read_b128 v[176:179], v169 offset:49152
	ds_read_b128 v[214:217], v169 offset:57344
	ds_read_b128 v[218:221], v170 offset:49152
	ds_read_b128 v[222:225], v170 offset:57344
	ds_read_b128 v[226:229], v171 offset:49152
	ds_read_b128 v[230:233], v171 offset:57344
	ds_read_b128 v[234:237], v172 offset:49152
	ds_read_b128 v[238:241], v172 offset:57344
	s_waitcnt lgkmcnt(10)
	v_mfma_f32_32x32x16_bf16 v[64:79], v[198:201], v[120:123], v[64:79]
	ds_read_b128 v[198:201], v173 offset:49152
	ds_read_b128 v[242:245], v173 offset:57344
	s_waitcnt lgkmcnt(11)
	v_mfma_f32_32x32x16_bf16 v[80:95], v[202:205], v[112:115], v[80:95]
	v_exp_f32_e32 v205, v134
	v_add_f32_e32 v134, v191, v190
	v_add_f32_e32 v134, v192, v134
	v_add_f32_e32 v134, v193, v134
	v_add_f32_e32 v134, v194, v134
	v_add_f32_e32 v134, v196, v134
	s_waitcnt lgkmcnt(10)
	v_mfma_f32_32x32x16_bf16 v[64:79], v[210:213], v[112:115], v[64:79]
	v_add_f32_e32 v134, v195, v134
	v_add_f32_e32 v134, v197, v134
	v_add_f32_e32 v134, v182, v134
	v_add_f32_e32 v134, v183, v134
	v_add_f32_e32 v134, v184, v134
	v_add_f32_e32 v134, v186, v134
	v_add_f32_e32 v134, v185, v134
	s_waitcnt lgkmcnt(9)
	v_mfma_f32_32x32x16_bf16 v[80:95], v[176:179], v[116:119], v[80:95]
	v_add_f32_e32 v134, v187, v134
	v_add_f32_e32 v134, v188, v134
	v_add_f32_e32 v134, v189, v134
	v_add_f32_e32 v134, v142, v134
	v_exp_f32_e32 v202, v139
	v_add_f32_e32 v134, v143, v134
	v_exp_f32_e32 v203, v136
	s_waitcnt lgkmcnt(8)
	v_mfma_f32_32x32x16_bf16 v[64:79], v[214:217], v[116:119], v[64:79]
	v_add_f32_e32 v134, v180, v134
	v_exp_f32_e32 v204, v137
	v_add_f32_e32 v134, v181, v134
	v_add_f32_e32 v134, v206, v134
	v_add_f32_e32 v134, v202, v134
	v_add_f32_e32 v134, v203, v134
	v_add_f32_e32 v134, v204, v134
	s_waitcnt lgkmcnt(7)
	v_mfma_f32_32x32x16_bf16 v[80:95], v[218:221], v[108:111], v[80:95]
	v_add_f32_e32 v134, v205, v134
	v_exp_f32_e32 v210, v147
	v_add_f32_e32 v134, v207, v134
	v_exp_f32_e32 v211, v144
	v_add_f32_e32 v134, v148, v134
	v_exp_f32_e32 v212, v145
	v_add_f32_e32 v134, v149, v134
	s_waitcnt lgkmcnt(6)
	v_mfma_f32_32x32x16_bf16 v[64:79], v[222:225], v[108:111], v[64:79]
	v_add_f32_e32 v134, v209, v134
	v_add_f32_e32 v134, v210, v134
	v_add_f32_e32 v134, v211, v134
	v_add_f32_e32 v176, v212, v134
	v_cvt_pk_bf16_f32 v134, v190, v191
	v_cvt_pk_bf16_f32 v136, v194, v196
	s_waitcnt lgkmcnt(5)
	v_mfma_f32_32x32x16_bf16 v[80:95], v[226:229], v[104:107], v[80:95]
	v_cvt_pk_bf16_f32 v137, v195, v197
	v_cvt_pk_bf16_f32 v139, v184, v186
	v_cvt_pk_bf16_f32 v142, v142, v143
	s_waitcnt lgkmcnt(4)
	v_mfma_f32_32x32x16_bf16 v[64:79], v[230:233], v[104:107], v[64:79]
	v_cvt_pk_bf16_f32 v143, v180, v181
	v_cvt_pk_bf16_f32 v144, v206, v202
	v_cvt_pk_bf16_f32 v145, v203, v204
	v_cvt_pk_bf16_f32 v146, v205, v207
	v_cvt_pk_bf16_f32 v147, v148, v149
	v_cvt_pk_bf16_f32 v148, v209, v210
	v_cvt_pk_bf16_f32 v149, v211, v212
	s_waitcnt lgkmcnt(3)
	v_mfma_f32_32x32x16_bf16 v[80:95], v[234:237], v[100:103], v[80:95]
	s_waitcnt lgkmcnt(2)
	v_mfma_f32_32x32x16_bf16 v[64:79], v[238:241], v[100:103], v[64:79]
	s_waitcnt lgkmcnt(1)
	v_mfma_f32_32x32x16_bf16 v[80:95], v[198:201], v[96:99], v[80:95]
	s_waitcnt lgkmcnt(0)
	v_mfma_f32_32x32x16_bf16 v[64:79], v[242:245], v[96:99], v[64:79]
	global_load_dwordx4 v[218:221], v132, s[28:29]
	global_load_dwordx4 v[222:225], v133, s[28:29]
	global_load_dwordx4 v[226:229], v132, s[30:31]
	global_load_dwordx4 v[230:233], v133, s[30:31]
	s_add_u32 s28, s28, 0x8000
	s_addc_u32 s29, s29, 0
	s_add_u32 s30, s30, 0x8000
	s_addc_u32 s31, s31, 0
	ds_read_b64_tr_b16 v[196:197], v161 offset:0
	ds_read_b64_tr_b16 v[198:199], v161 offset:0x800
	ds_read_b64_tr_b16 v[200:201], v161 offset:0x1000
	ds_read_b64_tr_b16 v[202:203], v161 offset:0x1800
	ds_read_b64_tr_b16 v[204:205], v161 offset:0x2000
	ds_read_b64_tr_b16 v[206:207], v161 offset:0x2800
	ds_read_b64_tr_b16 v[210:211], v161 offset:0x3000
	ds_read_b64_tr_b16 v[212:213], v161 offset:0x3800
	s_waitcnt lgkmcnt(0)
	s_nop 0
	v_mfma_f32_32x32x16_bf16 v[0:15], v[134:137], v[196:199], v[0:15]
	ds_read_b64_tr_b16 v[196:197], v161 offset:0x200
	ds_read_b64_tr_b16 v[198:199], v161 offset:0xa00
	v_max_f32_e32 v234, v80, v81
	v_max3_f32 v234, v234, v82, v83
	v_max3_f32 v234, v234, v84, v85
	v_max3_f32 v234, v234, v86, v87
	v_max3_f32 v234, v234, v88, v89
	v_mfma_f32_32x32x16_bf16 v[0:15], v[138:141], v[200:203], v[0:15]
	ds_read_b64_tr_b16 v[200:201], v161 offset:0x1200
	ds_read_b64_tr_b16 v[202:203], v161 offset:0x1a00
	v_max3_f32 v234, v234, v90, v91
	v_max3_f32 v234, v234, v92, v93
	v_max3_f32 v234, v234, v94, v95
	v_max3_f32 v234, v234, v64, v65
	v_max3_f32 v234, v234, v66, v67
	v_mfma_f32_32x32x16_bf16 v[0:15], v[142:145], v[204:207], v[0:15]
	ds_read_b64_tr_b16 v[204:205], v161 offset:0x2200
	ds_read_b64_tr_b16 v[206:207], v161 offset:0x2a00
	ds_read_b64_tr_b16 v[214:215], v161 offset:0x3200
	ds_read_b64_tr_b16 v[216:217], v161 offset:0x3a00
	v_max3_f32 v234, v234, v68, v69
	v_max3_f32 v234, v234, v70, v71
	v_max3_f32 v234, v234, v72, v73
	v_max3_f32 v234, v234, v74, v75
	v_max3_f32 v234, v234, v76, v77
	s_waitcnt lgkmcnt(0)
	v_mfma_f32_32x32x16_bf16 v[0:15], v[146:149], v[210:213], v[0:15]
	v_max3_f32 v234, v234, v78, v79
	v_mov_b32_e32 v235, v234
	v_mfma_f32_32x32x16_bf16 v[48:63], v[134:137], v[196:199], v[48:63]
	ds_read_b64_tr_b16 v[196:197], v161 offset:0x400
	ds_read_b64_tr_b16 v[198:199], v161 offset:0xc00
	v_permlane32_swap_b32_e32 v234, v235
	v_max_f32_e32 v234, v234, v235
	v_mfma_f32_32x32x16_bf16 v[48:63], v[138:141], v[200:203], v[48:63]
	ds_read_b64_tr_b16 v[200:201], v161 offset:0x1400
	ds_read_b64_tr_b16 v[202:203], v161 offset:0x1c00
	v_sub_f32_e32 v235, v234, v175
	v_max_f32_e32 v234, v175, v234
	v_sub_f32_e32 v236, v175, v234
	v_mul_f32_e32 v236, 0x3e0293ee, v236
	v_mfma_f32_32x32x16_bf16 v[48:63], v[142:145], v[204:207], v[48:63]
	ds_read_b64_tr_b16 v[204:205], v161 offset:0x2400
	ds_read_b64_tr_b16 v[206:207], v161 offset:0x2c00
	ds_read_b64_tr_b16 v[210:211], v161 offset:0x3400
	ds_read_b64_tr_b16 v[212:213], v161 offset:0x3c00
	v_exp_f32_e32 v236, v236
	v_cmp_ge_f32_e32 vcc, s15, v235
	s_cmp_eq_u64 vcc, exec
	s_cselect_b64 s[8:9], -1, 0
	s_waitcnt lgkmcnt(0)
	v_mfma_f32_32x32x16_bf16 v[48:63], v[146:149], v[214:217], v[48:63]
	v_cndmask_b32_e64 v179, v236, 1.0, s[8:9]
	v_cndmask_b32_e64 v234, v234, v175, s[8:9]
	v_mul_f32_e32 v238, 0xbe0293ee, v234
	v_fmamk_f32 v88, v88, 0x3e0293ee, v238
	v_fmamk_f32 v89, v89, 0x3e0293ee, v238
	v_fmamk_f32 v80, v80, 0x3e0293ee, v238
	v_fmamk_f32 v81, v81, 0x3e0293ee, v238
	v_mfma_f32_32x32x16_bf16 v[32:47], v[134:137], v[196:199], v[32:47]
	ds_read_b64_tr_b16 v[196:197], v161 offset:0x600
	ds_read_b64_tr_b16 v[198:199], v161 offset:0xe00
	v_fmamk_f32 v82, v82, 0x3e0293ee, v238
	v_fmamk_f32 v83, v83, 0x3e0293ee, v238
	v_fmamk_f32 v84, v84, 0x3e0293ee, v238
	v_fmamk_f32 v85, v85, 0x3e0293ee, v238
	v_fmamk_f32 v86, v86, 0x3e0293ee, v238
	v_fmamk_f32 v87, v87, 0x3e0293ee, v238
	v_fmamk_f32 v90, v90, 0x3e0293ee, v238
	v_fmamk_f32 v91, v91, 0x3e0293ee, v238
	v_mfma_f32_32x32x16_bf16 v[32:47], v[138:141], v[200:203], v[32:47]
	ds_read_b64_tr_b16 v[200:201], v161 offset:0x1600
	ds_read_b64_tr_b16 v[202:203], v161 offset:0x1e00
	v_fmamk_f32 v92, v92, 0x3e0293ee, v238
	v_fmamk_f32 v93, v93, 0x3e0293ee, v238
	v_fmamk_f32 v94, v94, 0x3e0293ee, v238
	v_fmamk_f32 v95, v95, 0x3e0293ee, v238
	v_fmamk_f32 v188, v64, 0x3e0293ee, v238
	v_fmamk_f32 v189, v65, 0x3e0293ee, v238
	v_fmamk_f32 v190, v66, 0x3e0293ee, v238
	v_fmamk_f32 v191, v67, 0x3e0293ee, v238
	v_mfma_f32_32x32x16_bf16 v[32:47], v[142:145], v[204:207], v[32:47]
	ds_read_b64_tr_b16 v[204:205], v161 offset:0x2600
	ds_read_b64_tr_b16 v[206:207], v161 offset:0x2e00
	ds_read_b64_tr_b16 v[214:215], v161 offset:0x3600
	ds_read_b64_tr_b16 v[216:217], v161 offset:0x3e00
	v_fmamk_f32 v182, v70, 0x3e0293ee, v238
	v_fmamk_f32 v183, v71, 0x3e0293ee, v238
	v_fmamk_f32 v184, v72, 0x3e0293ee, v238
	v_fmamk_f32 v185, v73, 0x3e0293ee, v238
	v_fmamk_f32 v186, v74, 0x3e0293ee, v238
	v_fmamk_f32 v187, v75, 0x3e0293ee, v238
	s_waitcnt lgkmcnt(0)
	v_mfma_f32_32x32x16_bf16 v[32:47], v[146:149], v[210:213], v[32:47]
	v_fmamk_f32 v192, v68, 0x3e0293ee, v238
	v_fmamk_f32 v181, v69, 0x3e0293ee, v238
	v_fmamk_f32 v180, v76, 0x3e0293ee, v238
	v_mfma_f32_32x32x16_bf16 v[16:31], v[134:137], v[196:199], v[16:31]
	v_fmamk_f32 v193, v77, 0x3e0293ee, v238
	v_fmamk_f32 v194, v78, 0x3e0293ee, v238
	v_fmamk_f32 v177, v79, 0x3e0293ee, v238
	v_mov_b32_e32 v134, v234
	v_exp_f32_e32 v135, v88
	v_exp_f32_e32 v136, v89
	v_exp_f32_e32 v137, v90
	v_mfma_f32_32x32x16_bf16 v[16:31], v[138:141], v[200:203], v[16:31]
	v_exp_f32_e32 v139, v91
	v_exp_f32_e32 v138, v92
	v_exp_f32_e32 v140, v93
	v_exp_f32_e32 v141, v94
	v_mfma_f32_32x32x16_bf16 v[16:31], v[142:145], v[204:207], v[16:31]
	v_exp_f32_e32 v142, v95
	v_exp_f32_e32 v143, v80
	v_exp_f32_e32 v144, v81
	v_exp_f32_e32 v145, v82
	v_mfma_f32_32x32x16_bf16 v[16:31], v[146:149], v[214:217], v[16:31]
	v_exp_f32_e32 v146, v83
	v_exp_f32_e32 v147, v84
	v_exp_f32_e32 v149, v85
	v_exp_f32_e32 v148, v86
	v_exp_f32_e32 v175, v87
	v_cmp_gt_f32_e32 vcc, 1.0, v179
	s_barrier
	s_waitcnt vmcnt(0)
	ds_write_b128 v164, v[218:221]
	ds_write_b128 v165, v[222:225]
	ds_write_b128 v162, v[226:229] offset:32768
	ds_write_b128 v163, v[230:233] offset:32768
	s_cbranch_vccz .LBB0_437
	s_and_saveexec_b64 s[2:3], s[6:7]
	ds_write_b32 v158, v179 offset:128
	s_or_b64 exec, exec, s[2:3]
	s_waitcnt lgkmcnt(0)
	v_add_u32_e32 v234, v131, v128
	ds_read_b128 v[218:221], v234 offset:224
	ds_read_b128 v[222:225], v234 offset:192
	ds_read_b128 v[226:229], v234 offset:160
	ds_read_b128 v[230:233], v234 offset:128
	s_waitcnt lgkmcnt(3)
	v_pk_mul_f32 v[12:13], v[12:13], v[218:219]
	s_waitcnt lgkmcnt(2)
	v_pk_mul_f32 v[8:9], v[8:9], v[222:223]
	s_waitcnt lgkmcnt(1)
	v_pk_mul_f32 v[4:5], v[4:5], v[226:227]
	v_pk_mul_f32 v[14:15], v[14:15], v[220:221]
	v_pk_mul_f32 v[10:11], v[10:11], v[224:225]
	v_pk_mul_f32 v[6:7], v[6:7], v[228:229]
	s_waitcnt lgkmcnt(0)
	v_pk_mul_f32 v[2:3], v[2:3], v[232:233]
	v_pk_mul_f32 v[0:1], v[0:1], v[230:231]
	v_pk_mul_f32 v[60:61], v[60:61], v[218:219]
	v_pk_mul_f32 v[56:57], v[56:57], v[222:223]
	v_pk_mul_f32 v[52:53], v[52:53], v[226:227]
	v_pk_mul_f32 v[62:63], v[62:63], v[220:221]
	v_pk_mul_f32 v[58:59], v[58:59], v[224:225]
	v_pk_mul_f32 v[54:55], v[54:55], v[228:229]
	v_pk_mul_f32 v[50:51], v[50:51], v[232:233]
	v_pk_mul_f32 v[48:49], v[48:49], v[230:231]
	v_pk_mul_f32 v[44:45], v[44:45], v[218:219]
	v_pk_mul_f32 v[40:41], v[40:41], v[222:223]
	v_pk_mul_f32 v[36:37], v[36:37], v[226:227]
	v_pk_mul_f32 v[46:47], v[46:47], v[220:221]
	v_pk_mul_f32 v[42:43], v[42:43], v[224:225]
	v_pk_mul_f32 v[38:39], v[38:39], v[228:229]
	v_pk_mul_f32 v[34:35], v[34:35], v[232:233]
	v_pk_mul_f32 v[32:33], v[32:33], v[230:231]
	v_pk_mul_f32 v[28:29], v[28:29], v[218:219]
	v_pk_mul_f32 v[24:25], v[24:25], v[222:223]
	v_pk_mul_f32 v[20:21], v[20:21], v[226:227]
	v_pk_mul_f32 v[30:31], v[30:31], v[220:221]
	v_pk_mul_f32 v[26:27], v[26:27], v[224:225]
	v_pk_mul_f32 v[22:23], v[22:23], v[228:229]
	v_pk_mul_f32 v[18:19], v[18:19], v[232:233]
	v_pk_mul_f32 v[16:17], v[16:17], v[230:231]
.LBB0_437:
	s_waitcnt lgkmcnt(0)
	s_barrier
	ds_read_b128 v[64:67], v166 offset:32768
	ds_read_b128 v[68:71], v166 offset:40960
	ds_read_b128 v[196:199], v167 offset:32768
	ds_read_b128 v[200:203], v167 offset:40960
	ds_read_b128 v[204:207], v168 offset:32768
	ds_read_b128 v[210:213], v168 offset:40960
	v_exp_f32_e32 v188, v188
	v_exp_f32_e32 v189, v189
	s_waitcnt lgkmcnt(5)
	v_mfma_f32_32x32x16_bf16 v[80:95], v[64:67], v[124:127], 0
	v_exp_f32_e32 v190, v190
	v_exp_f32_e32 v191, v191
	v_exp_f32_e32 v192, v192
	v_exp_f32_e32 v195, v181
	v_exp_f32_e32 v182, v182
	v_exp_f32_e32 v183, v183
	v_exp_f32_e32 v184, v184
	s_waitcnt lgkmcnt(4)
	v_mfma_f32_32x32x16_bf16 v[64:79], v[68:71], v[124:127], 0
	v_exp_f32_e32 v185, v185
	v_exp_f32_e32 v186, v186
	v_exp_f32_e32 v187, v187
	v_exp_f32_e32 v193, v193
	v_exp_f32_e32 v194, v194
	v_exp_f32_e32 v177, v177
	s_waitcnt lgkmcnt(3)
	v_mfma_f32_32x32x16_bf16 v[80:95], v[196:199], v[120:123], v[80:95]
	ds_read_b128 v[196:199], v169 offset:32768
	ds_read_b128 v[214:217], v169 offset:40960
	ds_read_b128 v[218:221], v170 offset:32768
	ds_read_b128 v[222:225], v170 offset:40960
	ds_read_b128 v[226:229], v171 offset:32768
	ds_read_b128 v[230:233], v171 offset:40960
	ds_read_b128 v[234:237], v172 offset:32768
	ds_read_b128 v[238:241], v172 offset:40960
	s_waitcnt lgkmcnt(10)
	v_mfma_f32_32x32x16_bf16 v[64:79], v[200:203], v[120:123], v[64:79]
	ds_read_b128 v[200:203], v173 offset:32768
	ds_read_b128 v[242:245], v173 offset:40960
	s_waitcnt lgkmcnt(11)
	v_mfma_f32_32x32x16_bf16 v[80:95], v[204:207], v[112:115], v[80:95]
	v_exp_f32_e32 v204, v180
	v_add_f32_e32 v180, v144, v143
	v_add_f32_e32 v180, v145, v180
	v_add_f32_e32 v180, v146, v180
	v_add_f32_e32 v180, v147, v180
	v_add_f32_e32 v180, v149, v180
	s_waitcnt lgkmcnt(10)
	v_mfma_f32_32x32x16_bf16 v[64:79], v[210:213], v[112:115], v[64:79]
	v_add_f32_e32 v180, v148, v180
	v_add_f32_e32 v180, v175, v180
	v_add_f32_e32 v180, v135, v180
	v_add_f32_e32 v180, v136, v180
	v_add_f32_e32 v180, v137, v180
	v_add_f32_e32 v180, v139, v180
	v_add_f32_e32 v180, v138, v180
	s_waitcnt lgkmcnt(9)
	v_mfma_f32_32x32x16_bf16 v[80:95], v[196:199], v[116:119], v[80:95]
	v_add_f32_e32 v180, v140, v180
	v_add_f32_e32 v180, v141, v180
	v_add_f32_e32 v180, v142, v180
	v_add_f32_e32 v180, v188, v180
	v_add_f32_e32 v180, v189, v180
	v_add_f32_e32 v180, v190, v180
	v_add_f32_e32 v180, v191, v180
	s_waitcnt lgkmcnt(8)
	v_mfma_f32_32x32x16_bf16 v[64:79], v[214:217], v[116:119], v[64:79]
	v_add_f32_e32 v180, v192, v180
	v_add_f32_e32 v180, v195, v180
	v_add_f32_e32 v180, v182, v180
	v_add_f32_e32 v180, v183, v180
	v_add_f32_e32 v180, v184, v180
	v_add_f32_e32 v180, v185, v180
	v_add_f32_e32 v180, v186, v180
	s_waitcnt lgkmcnt(7)
	v_mfma_f32_32x32x16_bf16 v[80:95], v[218:221], v[108:111], v[80:95]
	v_add_f32_e32 v180, v187, v180
	v_add_f32_e32 v180, v204, v180
	v_add_f32_e32 v180, v193, v180
	v_add_f32_e32 v180, v194, v180
	v_add_f32_e32 v180, v177, v180
	s_waitcnt lgkmcnt(6)
	v_mfma_f32_32x32x16_bf16 v[64:79], v[222:225], v[108:111], v[64:79]
	v_cvt_pk_bf16_f32 v144, v143, v144
	v_cvt_pk_bf16_f32 v145, v145, v146
	v_cvt_pk_bf16_f32 v146, v147, v149
	v_cvt_pk_bf16_f32 v147, v148, v175
	v_cvt_pk_bf16_f32 v136, v135, v136
	v_cvt_pk_bf16_f32 v137, v137, v139
	v_cvt_pk_bf16_f32 v138, v138, v140
	s_waitcnt lgkmcnt(5)
	v_mfma_f32_32x32x16_bf16 v[80:95], v[226:229], v[104:107], v[80:95]
	v_cvt_pk_bf16_f32 v139, v141, v142
	v_cvt_pk_bf16_f32 v140, v188, v189
	v_cvt_pk_bf16_f32 v141, v190, v191
	v_cvt_pk_bf16_f32 v142, v192, v195
	v_cvt_pk_bf16_f32 v143, v182, v183
	v_cvt_pk_bf16_f32 v182, v184, v185
	v_cvt_pk_bf16_f32 v183, v186, v187
	s_waitcnt lgkmcnt(4)
	v_mfma_f32_32x32x16_bf16 v[64:79], v[230:233], v[104:107], v[64:79]
	v_cvt_pk_bf16_f32 v184, v204, v193
	v_cvt_pk_bf16_f32 v185, v194, v177
	s_waitcnt lgkmcnt(3)
	v_mfma_f32_32x32x16_bf16 v[80:95], v[234:237], v[100:103], v[80:95]
	s_waitcnt lgkmcnt(2)
	v_mfma_f32_32x32x16_bf16 v[64:79], v[238:241], v[100:103], v[64:79]
	s_waitcnt lgkmcnt(1)
	v_mfma_f32_32x32x16_bf16 v[80:95], v[200:203], v[96:99], v[80:95]
	s_waitcnt lgkmcnt(0)
	v_mfma_f32_32x32x16_bf16 v[64:79], v[242:245], v[96:99], v[64:79]
	global_load_dwordx4 v[226:229], v132, s[28:29]
	global_load_dwordx4 v[230:233], v132, s[30:31]
	global_load_dwordx4 v[234:237], v133, s[28:29]
	global_load_dwordx4 v[238:241], v133, s[30:31]
	s_add_u32 s28, s28, 0x8000
	s_addc_u32 s29, s29, 0
	s_add_u32 s30, s30, 0x8000
	s_addc_u32 s31, s31, 0
	ds_read_b64_tr_b16 v[202:203], v160 offset:0
	ds_read_b64_tr_b16 v[204:205], v160 offset:0x800
	ds_read_b64_tr_b16 v[210:211], v160 offset:0x1000
	ds_read_b64_tr_b16 v[212:213], v160 offset:0x1800
	ds_read_b64_tr_b16 v[214:215], v160 offset:0x2000
	ds_read_b64_tr_b16 v[216:217], v160 offset:0x2800
	ds_read_b64_tr_b16 v[218:219], v160 offset:0x3000
	ds_read_b64_tr_b16 v[220:221], v160 offset:0x3800
	s_waitcnt lgkmcnt(0)
	s_nop 0
	v_mfma_f32_32x32x16_bf16 v[0:15], v[144:147], v[202:205], v[0:15]
	ds_read_b64_tr_b16 v[202:203], v160 offset:0x200
	ds_read_b64_tr_b16 v[204:205], v160 offset:0xa00
	v_max_f32_e32 v242, v80, v81
	v_max3_f32 v242, v242, v82, v83
	v_max3_f32 v242, v242, v84, v85
	v_max3_f32 v242, v242, v86, v87
	v_max3_f32 v242, v242, v88, v89
	v_mfma_f32_32x32x16_bf16 v[0:15], v[136:139], v[210:213], v[0:15]
	ds_read_b64_tr_b16 v[210:211], v160 offset:0x1200
	ds_read_b64_tr_b16 v[212:213], v160 offset:0x1a00
	v_max3_f32 v242, v242, v90, v91
	v_max3_f32 v242, v242, v92, v93
	v_max3_f32 v242, v242, v94, v95
	v_max3_f32 v242, v242, v64, v65
	v_max3_f32 v242, v242, v66, v67
	v_mfma_f32_32x32x16_bf16 v[0:15], v[140:143], v[214:217], v[0:15]
	ds_read_b64_tr_b16 v[214:215], v160 offset:0x2200
	ds_read_b64_tr_b16 v[216:217], v160 offset:0x2a00
	ds_read_b64_tr_b16 v[222:223], v160 offset:0x3200
	ds_read_b64_tr_b16 v[224:225], v160 offset:0x3a00
	v_max3_f32 v242, v242, v68, v69
	v_max3_f32 v242, v242, v70, v71
	v_max3_f32 v242, v242, v72, v73
	v_max3_f32 v242, v242, v74, v75
	v_max3_f32 v242, v242, v76, v77
	s_waitcnt lgkmcnt(0)
	v_mfma_f32_32x32x16_bf16 v[0:15], v[182:185], v[218:221], v[0:15]
	v_max3_f32 v242, v242, v78, v79
	v_mov_b32_e32 v243, v242
	v_mfma_f32_32x32x16_bf16 v[48:63], v[144:147], v[202:205], v[48:63]
	ds_read_b64_tr_b16 v[202:203], v160 offset:0x400
	ds_read_b64_tr_b16 v[204:205], v160 offset:0xc00
	v_permlane32_swap_b32_e32 v242, v243
	v_max_f32_e32 v242, v242, v243
	v_mfma_f32_32x32x16_bf16 v[48:63], v[136:139], v[210:213], v[48:63]
	ds_read_b64_tr_b16 v[210:211], v160 offset:0x1400
	ds_read_b64_tr_b16 v[212:213], v160 offset:0x1c00
	v_sub_f32_e32 v243, v242, v134
	v_max_f32_e32 v242, v134, v242
	v_sub_f32_e32 v148, v134, v242
	v_mul_f32_e32 v148, 0x3e0293ee, v148
	v_mfma_f32_32x32x16_bf16 v[48:63], v[140:143], v[214:217], v[48:63]
	ds_read_b64_tr_b16 v[214:215], v160 offset:0x2400
	ds_read_b64_tr_b16 v[216:217], v160 offset:0x2c00
	ds_read_b64_tr_b16 v[218:219], v160 offset:0x3400
	ds_read_b64_tr_b16 v[220:221], v160 offset:0x3c00
	v_exp_f32_e32 v148, v148
	v_cmp_ge_f32_e32 vcc, s15, v243
	s_cmp_eq_u64 vcc, exec
	s_cselect_b64 s[8:9], -1, 0
	s_waitcnt lgkmcnt(0)
	v_mfma_f32_32x32x16_bf16 v[48:63], v[182:185], v[222:225], v[48:63]
	v_cndmask_b32_e64 v177, v148, 1.0, s[8:9]
	v_cndmask_b32_e64 v175, v242, v134, s[8:9]
	v_mul_f32_e32 v244, 0xbe0293ee, v175
	v_fmamk_f32 v80, v80, 0x3e0293ee, v244
	v_fmamk_f32 v81, v81, 0x3e0293ee, v244
	v_fmamk_f32 v82, v82, 0x3e0293ee, v244
	v_fmamk_f32 v83, v83, 0x3e0293ee, v244
	v_mfma_f32_32x32x16_bf16 v[32:47], v[144:147], v[202:205], v[32:47]
	ds_read_b64_tr_b16 v[202:203], v160 offset:0x600
	ds_read_b64_tr_b16 v[204:205], v160 offset:0xe00
	v_fmamk_f32 v84, v84, 0x3e0293ee, v244
	v_fmamk_f32 v85, v85, 0x3e0293ee, v244
	v_fmamk_f32 v86, v86, 0x3e0293ee, v244
	v_fmamk_f32 v87, v87, 0x3e0293ee, v244
	v_fmamk_f32 v88, v88, 0x3e0293ee, v244
	v_fmamk_f32 v89, v89, 0x3e0293ee, v244
	v_fmamk_f32 v90, v90, 0x3e0293ee, v244
	v_fmamk_f32 v91, v91, 0x3e0293ee, v244
	v_mfma_f32_32x32x16_bf16 v[32:47], v[136:139], v[210:213], v[32:47]
	ds_read_b64_tr_b16 v[210:211], v160 offset:0x1600
	ds_read_b64_tr_b16 v[212:213], v160 offset:0x1e00
	v_fmamk_f32 v92, v92, 0x3e0293ee, v244
	v_fmamk_f32 v93, v93, 0x3e0293ee, v244
	v_fmamk_f32 v94, v94, 0x3e0293ee, v244
	v_fmamk_f32 v95, v95, 0x3e0293ee, v244
	v_fmamk_f32 v134, v72, 0x3e0293ee, v244
	v_fmamk_f32 v135, v73, 0x3e0293ee, v244
	v_fmamk_f32 v148, v74, 0x3e0293ee, v244
	v_fmamk_f32 v149, v75, 0x3e0293ee, v244
	v_mfma_f32_32x32x16_bf16 v[32:47], v[140:143], v[214:217], v[32:47]
	ds_read_b64_tr_b16 v[214:215], v160 offset:0x2600
	ds_read_b64_tr_b16 v[216:217], v160 offset:0x2e00
	ds_read_b64_tr_b16 v[222:223], v160 offset:0x3600
	ds_read_b64_tr_b16 v[224:225], v160 offset:0x3e00
	v_exp_f32_e32 v190, v80
	v_exp_f32_e32 v191, v81
	v_exp_f32_e32 v192, v82
	s_waitcnt lgkmcnt(0)
	v_mfma_f32_32x32x16_bf16 v[32:47], v[182:185], v[218:221], v[32:47]
	v_exp_f32_e32 v193, v83
	v_exp_f32_e32 v194, v84
	v_exp_f32_e32 v196, v85
	v_mfma_f32_32x32x16_bf16 v[16:31], v[144:147], v[202:205], v[16:31]
	v_fmamk_f32 v144, v78, 0x3e0293ee, v244
	v_fmamk_f32 v145, v79, 0x3e0293ee, v244
	v_fmamk_f32 v146, v76, 0x3e0293ee, v244
	v_fmamk_f32 v147, v77, 0x3e0293ee, v244
	v_exp_f32_e32 v195, v86
	v_exp_f32_e32 v197, v87
	v_mfma_f32_32x32x16_bf16 v[16:31], v[136:139], v[210:213], v[16:31]
	v_fmamk_f32 v136, v70, 0x3e0293ee, v244
	v_fmamk_f32 v137, v71, 0x3e0293ee, v244
	v_fmamk_f32 v138, v68, 0x3e0293ee, v244
	v_fmamk_f32 v139, v69, 0x3e0293ee, v244
	v_exp_f32_e32 v186, v91
	v_exp_f32_e32 v187, v93
	v_mfma_f32_32x32x16_bf16 v[16:31], v[140:143], v[214:217], v[16:31]
	v_fmamk_f32 v140, v66, 0x3e0293ee, v244
	v_fmamk_f32 v141, v67, 0x3e0293ee, v244
	v_fmamk_f32 v142, v64, 0x3e0293ee, v244
	v_fmamk_f32 v143, v65, 0x3e0293ee, v244
	v_exp_f32_e32 v188, v94
	v_exp_f32_e32 v189, v95
	v_mfma_f32_32x32x16_bf16 v[16:31], v[182:185], v[222:225], v[16:31]
	v_exp_f32_e32 v182, v88
	v_exp_f32_e32 v183, v89
	v_exp_f32_e32 v184, v90
	v_exp_f32_e32 v185, v92
	v_cmp_gt_f32_e32 vcc, 1.0, v177
	s_barrier
	s_waitcnt vmcnt(0)
	ds_write_b128 v164, v[226:229] offset:16384
	ds_write_b128 v165, v[234:237] offset:16384
	ds_write_b128 v162, v[230:233] offset:49152
	ds_write_b128 v163, v[238:241] offset:49152
	s_cbranch_vccz .LBB0_441
	s_and_saveexec_b64 s[2:3], s[6:7]
	ds_write_b32 v158, v177 offset:128
	s_or_b64 exec, exec, s[2:3]
	s_waitcnt lgkmcnt(0)
	v_add_u32_e32 v242, v131, v128
	ds_read_b128 v[226:229], v242 offset:224
	ds_read_b128 v[230:233], v242 offset:192
	ds_read_b128 v[234:237], v242 offset:160
	ds_read_b128 v[238:241], v242 offset:128
	s_waitcnt lgkmcnt(3)
	v_pk_mul_f32 v[12:13], v[12:13], v[226:227]
	s_waitcnt lgkmcnt(2)
	v_pk_mul_f32 v[8:9], v[8:9], v[230:231]
	s_waitcnt lgkmcnt(1)
	v_pk_mul_f32 v[4:5], v[4:5], v[234:235]
	v_pk_mul_f32 v[14:15], v[14:15], v[228:229]
	v_pk_mul_f32 v[10:11], v[10:11], v[232:233]
	v_pk_mul_f32 v[6:7], v[6:7], v[236:237]
	s_waitcnt lgkmcnt(0)
	v_pk_mul_f32 v[2:3], v[2:3], v[240:241]
	v_pk_mul_f32 v[0:1], v[0:1], v[238:239]
	v_pk_mul_f32 v[60:61], v[60:61], v[226:227]
	v_pk_mul_f32 v[56:57], v[56:57], v[230:231]
	v_pk_mul_f32 v[52:53], v[52:53], v[234:235]
	v_pk_mul_f32 v[62:63], v[62:63], v[228:229]
	v_pk_mul_f32 v[58:59], v[58:59], v[232:233]
	v_pk_mul_f32 v[54:55], v[54:55], v[236:237]
	v_pk_mul_f32 v[50:51], v[50:51], v[240:241]
	v_pk_mul_f32 v[48:49], v[48:49], v[238:239]
	v_pk_mul_f32 v[44:45], v[44:45], v[226:227]
	v_pk_mul_f32 v[40:41], v[40:41], v[230:231]
	v_pk_mul_f32 v[36:37], v[36:37], v[234:235]
	v_pk_mul_f32 v[46:47], v[46:47], v[228:229]
	v_pk_mul_f32 v[42:43], v[42:43], v[232:233]
	v_pk_mul_f32 v[38:39], v[38:39], v[236:237]
	v_pk_mul_f32 v[34:35], v[34:35], v[240:241]
	v_pk_mul_f32 v[32:33], v[32:33], v[238:239]
	v_pk_mul_f32 v[28:29], v[28:29], v[226:227]
	v_pk_mul_f32 v[24:25], v[24:25], v[230:231]
	v_pk_mul_f32 v[20:21], v[20:21], v[234:235]
	v_pk_mul_f32 v[30:31], v[30:31], v[228:229]
	v_pk_mul_f32 v[26:27], v[26:27], v[232:233]
	v_pk_mul_f32 v[22:23], v[22:23], v[236:237]
	v_pk_mul_f32 v[18:19], v[18:19], v[240:241]
	v_pk_mul_f32 v[16:17], v[16:17], v[238:239]
